# POOLMIX pooling: drop the mid-issue vmcnt(0) in each window variant (all row loads now issue back-to-back; counted wait before first use)
# speedup vs baseline: 1.0085x; 1.0034x over previous
.LBB0_331:
	s_add_i32 s2, s40, -11
	s_and_b64 s[18:19], s[26:27], exec
	s_cselect_b32 s6, 0x8005, -1
	s_and_b64 s[18:19], s[50:51], exec
	s_cselect_b32 s2, s6, s2
	s_cmp_gt_i32 s2, -1
	s_cselect_b32 s58, s2, s40
	s_ashr_i32 s59, s58, 31
	s_lshl_b64 s[18:19], s[58:59], 11
	v_lshl_add_u64 v[2:3], v[214:215], 0, s[18:19]
	global_load_dwordx2 v[38:39], v[2:3], off
	s_cmp_lt_i32 s2, 0
	v_mov_b32_e32 v24, 0
	v_mov_b32_e32 v46, 0
	s_cbranch_scc1 .LBB0_333
	s_lshl_b64 s[18:19], s[58:59], 2
	s_add_u32 s18, s86, s18
	s_addc_u32 s19, s87, s19
	global_load_dword v46, v1, s[18:19]

.LBB0_391:
	s_add_i32 s2, s40, -5
	s_and_b64 s[18:19], s[26:27], exec
	s_cselect_b32 s6, 0x800b, -1
	s_and_b64 s[18:19], s[50:51], exec
	s_cselect_b32 s2, s6, s2
	s_cmp_gt_i32 s2, -1
	s_cselect_b32 s58, s2, s40
	s_ashr_i32 s59, s58, 31
	s_lshl_b64 s[18:19], s[58:59], 11
	v_lshl_add_u64 v[2:3], v[214:215], 0, s[18:19]
	global_load_dwordx2 v[24:25], v[2:3], off
	s_cmp_lt_i32 s2, 0
	v_mov_b32_e32 v23, 0
	v_mov_b32_e32 v22, 0
	s_cbranch_scc1 .LBB0_393
	s_lshl_b64 s[18:19], s[58:59], 2
	s_add_u32 s18, s86, s18
	s_addc_u32 s19, s87, s19
	global_load_dword v22, v1, s[18:19]

.LBB0_433:
	s_waitcnt vmcnt(20)
	v_lshlrev_b32_e32 v71, 16, v28
	v_lshlrev_b32_e32 v70, 16, v12
	v_pk_mul_f32 v[74:75], v[10:11], v[70:71]
	v_and_b32_e32 v71, 0xffff0000, v28
	v_and_b32_e32 v70, 0xffff0000, v12
	v_pk_mul_f32 v[76:77], v[10:11], v[70:71]
	v_lshlrev_b32_e32 v71, 16, v29
	v_lshlrev_b32_e32 v70, 16, v13
	v_pk_mul_f32 v[78:79], v[10:11], v[70:71]
	v_and_b32_e32 v29, 0xffff0000, v29
	v_add_f32_e32 v28, 0, v78
	v_add_f32_e32 v70, v28, v79
	v_and_b32_e32 v28, 0xffff0000, v13
	v_pk_mul_f32 v[28:29], v[10:11], v[28:29]
	s_waitcnt vmcnt(19)
	v_lshlrev_b32_e32 v11, 16, v40
	v_add_f32_e32 v10, 0, v28
	v_add_f32_e32 v13, v10, v29
	v_lshlrev_b32_e32 v10, 16, v24
	v_add_f32_e32 v12, 0, v76
	v_pk_mul_f32 v[80:81], v[22:23], v[10:11]
	v_and_b32_e32 v11, 0xffff0000, v40
	v_and_b32_e32 v10, 0xffff0000, v24
	v_add_f32_e32 v12, v12, v77
	v_pk_mul_f32 v[82:83], v[22:23], v[10:11]
	v_lshlrev_b32_e32 v11, 16, v41
	v_add_f32_e32 v10, v12, v82
	v_add_f32_e32 v12, v10, v83
	v_lshlrev_b32_e32 v10, 16, v25
	v_pk_mul_f32 v[84:85], v[22:23], v[10:11]
	v_and_b32_e32 v11, 0xffff0000, v41
	v_add_f32_e32 v10, v70, v84
	v_add_f32_e32 v24, v10, v85
	v_and_b32_e32 v10, 0xffff0000, v25
	v_pk_mul_f32 v[86:87], v[22:23], v[10:11]
	s_waitcnt vmcnt(17)
	v_lshlrev_b32_e32 v11, 16, v50
	v_add_f32_e32 v10, v13, v86
	v_add_f32_e32 v13, v10, v87
	v_lshlrev_b32_e32 v10, 16, v38
	v_pk_mul_f32 v[88:89], v[36:37], v[10:11]
	v_and_b32_e32 v11, 0xffff0000, v50
	v_and_b32_e32 v10, 0xffff0000, v38
	v_pk_mul_f32 v[90:91], v[36:37], v[10:11]
	v_lshlrev_b32_e32 v11, 16, v51
	v_add_f32_e32 v10, v12, v90
	v_add_f32_e32 v22, v10, v91
	v_lshlrev_b32_e32 v10, 16, v39
	v_pk_mul_f32 v[70:71], v[36:37], v[10:11]
	v_add_f32_e32 v0, 0, v74
	v_add_f32_e32 v10, v24, v70
	v_add_f32_e32 v38, v10, v71
	v_and_b32_e32 v11, 0xffff0000, v51
	v_and_b32_e32 v10, 0xffff0000, v39
	v_add_f32_e32 v0, v0, v75
	v_pk_mul_f32 v[50:51], v[36:37], v[10:11]
	v_add_f32_e32 v0, v0, v80
	v_add_f32_e32 v10, v13, v50
	s_waitcnt vmcnt(15)
	v_and_b32_e32 v13, 0xffff0000, v54
	v_and_b32_e32 v12, 0xffff0000, v48
	v_add_f32_e32 v0, v0, v81
	v_pk_mul_f32 v[12:13], v[46:47], v[12:13]
	v_add_f32_e32 v0, v0, v88
	v_add_f32_e32 v36, v10, v51
	v_lshlrev_b32_e32 v11, 16, v54
	v_lshlrev_b32_e32 v10, 16, v48
	v_add_f32_e32 v37, v22, v12
	v_lshlrev_b32_e32 v23, 16, v55
	v_lshlrev_b32_e32 v22, 16, v49
	v_add_f32_e32 v0, v0, v89
	s_cmpk_gt_i32 s40, 0x7fff
	v_pk_mul_f32 v[10:11], v[46:47], v[10:11]
	v_pk_mul_f32 v[24:25], v[46:47], v[22:23]
	v_and_b32_e32 v23, 0xffff0000, v55
	v_and_b32_e32 v22, 0xffff0000, v49
	v_add_f32_e32 v0, v0, v10
	v_add_f32_e32 v40, v38, v24
	v_pk_mul_f32 v[38:39], v[46:47], v[22:23]
	s_cselect_b64 vcc, -1, 0
	v_add_f32_e32 v22, v36, v38
	v_add_f32_e32 v36, v0, v11
	v_add_f32_e32 v37, v37, v13
	v_cndmask_b32_e64 v0, v240, 1.0, vcc
	v_add_f32_e32 v40, v40, v25
	v_add_f32_e32 v41, v22, v39
	v_fma_f32 v22, v0, v36, -v11
	v_fma_f32 v23, v0, v37, -v13
	v_cvt_pk_bf16_f32 v22, v22, v23
	v_fma_f32 v23, v0, v40, -v25
	v_fma_f32 v0, v0, v41, -v39
	s_mul_i32 s2, s16, 0x810
	v_cvt_pk_bf16_f32 v23, v23, v0
	v_add_u32_e32 v0, s2, v242
	ds_write_b64 v0, v[22:23]
	s_waitcnt vmcnt(6)
	v_lshlrev_b32_e32 v23, 16, v66
	v_lshlrev_b32_e32 v22, 16, v42
	v_sub_f32_e32 v36, v36, v74
	v_pk_mul_f32 v[22:23], v[44:45], v[22:23]
	v_sub_f32_e32 v46, v37, v76
	v_sub_f32_e32 v49, v41, v28
	v_add_f32_e32 v28, v36, v22
	v_and_b32_e32 v37, 0xffff0000, v66
	v_and_b32_e32 v36, 0xffff0000, v42
	v_cndmask_b32_e64 v54, v240, 0.5, vcc
	v_pk_mul_f32 v[36:37], v[44:45], v[36:37]
	v_sub_f32_e32 v48, v40, v78
	v_fma_f32 v40, v54, v28, -v22
	v_sub_f32_e32 v75, v28, v75
	v_add_f32_e32 v28, v46, v36
	v_fma_f32 v41, v54, v28, -v36
	v_sub_f32_e32 v66, v28, v77
	v_cvt_pk_bf16_f32 v28, v40, v41
	v_lshlrev_b32_e32 v41, 16, v67
	v_lshlrev_b32_e32 v40, 16, v43
	v_pk_mul_f32 v[46:47], v[44:45], v[40:41]
	v_and_b32_e32 v41, 0xffff0000, v67
	v_add_f32_e32 v40, v48, v46
	v_fma_f32 v48, v54, v40, -v46
	v_sub_f32_e32 v77, v40, v79
	v_and_b32_e32 v40, 0xffff0000, v43
	v_pk_mul_f32 v[42:43], v[44:45], v[40:41]
	v_cndmask_b32_e32 v55, v240, v235, vcc
	v_add_f32_e32 v40, v49, v42
	v_fma_f32 v41, v54, v40, -v42
	v_sub_f32_e32 v54, v40, v29
	v_cvt_pk_bf16_f32 v29, v48, v41
	ds_write_b64 v0, v[28:29] offset:2064
	s_waitcnt vmcnt(5)
	v_lshlrev_b32_e32 v29, 16, v64
	v_lshlrev_b32_e32 v28, 16, v34
	v_pk_mul_f32 v[28:29], v[26:27], v[28:29]
	v_and_b32_e32 v41, 0xffff0000, v64
	v_add_f32_e32 v40, v75, v28
	v_fma_f32 v44, v55, v40, -v28
	v_sub_f32_e32 v67, v40, v80
	v_and_b32_e32 v40, 0xffff0000, v34
	v_pk_mul_f32 v[40:41], v[26:27], v[40:41]
	v_and_b32_e32 v49, 0xffff0000, v65
	v_add_f32_e32 v34, v66, v40
	v_fma_f32 v45, v55, v34, -v40
	v_sub_f32_e32 v64, v34, v82
	v_cvt_pk_bf16_f32 v34, v44, v45
	v_lshlrev_b32_e32 v45, 16, v65
	v_lshlrev_b32_e32 v44, 16, v35
	v_pk_mul_f32 v[44:45], v[26:27], v[44:45]
	v_cndmask_b32_e32 v73, v240, v236, vcc
	v_add_f32_e32 v48, v77, v44
	v_fma_f32 v66, v55, v48, -v44
	v_sub_f32_e32 v75, v48, v84
	v_and_b32_e32 v48, 0xffff0000, v35
	v_pk_mul_f32 v[48:49], v[26:27], v[48:49]
	v_cndmask_b32_e32 v74, v240, v237, vcc
	v_add_f32_e32 v26, v54, v48
	v_fma_f32 v27, v55, v26, -v48
	v_sub_f32_e32 v65, v26, v86
	v_cvt_pk_bf16_f32 v35, v66, v27
	s_waitcnt vmcnt(4)
	v_lshlrev_b32_e32 v27, 16, v62
	v_lshlrev_b32_e32 v26, 16, v30
	v_pk_mul_f32 v[26:27], v[32:33], v[26:27]
	ds_write_b64 v0, v[34:35] offset:4128
	v_add_f32_e32 v34, v67, v26
	v_fma_f32 v54, v73, v34, -v26
	v_sub_f32_e32 v66, v34, v81
	v_and_b32_e32 v35, 0xffff0000, v62
	v_and_b32_e32 v34, 0xffff0000, v30
	v_pk_mul_f32 v[34:35], v[32:33], v[34:35]
	v_cndmask_b32_e32 v76, v240, v238, vcc
	v_add_f32_e32 v30, v64, v34
	v_fma_f32 v55, v73, v30, -v34
	v_sub_f32_e32 v64, v30, v83
	v_cvt_pk_bf16_f32 v30, v54, v55
	v_lshlrev_b32_e32 v55, 16, v63
	v_lshlrev_b32_e32 v54, 16, v31
	v_pk_mul_f32 v[54:55], v[32:33], v[54:55]
	v_and_b32_e32 v63, 0xffff0000, v63
	v_add_f32_e32 v62, v75, v54
	v_fma_f32 v67, v73, v62, -v54
	v_sub_f32_e32 v75, v62, v85
	v_and_b32_e32 v62, 0xffff0000, v31
	v_pk_mul_f32 v[32:33], v[32:33], v[62:63]
	s_waitcnt vmcnt(3)
	v_and_b32_e32 v63, 0xffff0000, v60
	v_add_f32_e32 v31, v65, v32
	v_fma_f32 v62, v73, v31, -v32
	v_sub_f32_e32 v73, v31, v87
	v_cvt_pk_bf16_f32 v31, v67, v62
	ds_write_b64 v0, v[30:31] offset:6192
	v_lshlrev_b32_e32 v31, 16, v60
	v_lshlrev_b32_e32 v30, 16, v20
	v_pk_mul_f32 v[30:31], v[14:15], v[30:31]
	v_cndmask_b32_e32 v78, v240, v239, vcc
	v_add_f32_e32 v62, v66, v30
	v_fma_f32 v65, v74, v62, -v30
	v_sub_f32_e32 v66, v62, v88
	v_and_b32_e32 v62, 0xffff0000, v20
	v_pk_mul_f32 v[62:63], v[14:15], v[62:63]
	v_lshlrev_b32_e32 v95, 16, v69
	v_add_f32_e32 v20, v64, v62
	v_fma_f32 v60, v74, v20, -v62
	v_sub_f32_e32 v67, v20, v90
	v_cvt_pk_bf16_f32 v20, v65, v60
	v_lshlrev_b32_e32 v65, 16, v61
	v_lshlrev_b32_e32 v64, 16, v21
	v_pk_mul_f32 v[64:65], v[14:15], v[64:65]
	v_and_b32_e32 v61, 0xffff0000, v61
	v_add_f32_e32 v60, v75, v64
	v_fma_f32 v75, v74, v60, -v64
	v_sub_f32_e32 v70, v60, v70
	v_and_b32_e32 v60, 0xffff0000, v21
	v_pk_mul_f32 v[14:15], v[14:15], v[60:61]
	s_waitcnt vmcnt(2)
	v_and_b32_e32 v61, 0xffff0000, v58
	v_add_f32_e32 v21, v73, v14
	v_fma_f32 v60, v74, v21, -v14
	v_sub_f32_e32 v50, v21, v50
	v_cvt_pk_bf16_f32 v21, v75, v60
	ds_write_b64 v0, v[20:21] offset:8256
	v_lshlrev_b32_e32 v21, 16, v58
	v_lshlrev_b32_e32 v20, 16, v16
	v_pk_mul_f32 v[20:21], v[18:19], v[20:21]
	v_and_b32_e32 v69, 0xffff0000, v69
	v_add_f32_e32 v60, v66, v20
	v_fma_f32 v66, v76, v60, -v20
	v_sub_f32_e32 v73, v60, v89
	v_and_b32_e32 v60, 0xffff0000, v16
	v_pk_mul_f32 v[60:61], v[18:19], v[60:61]
	v_mul_f32_e32 v97, v72, v69
	v_add_f32_e32 v16, v67, v60
	v_fma_f32 v58, v76, v16, -v60
	v_sub_f32_e32 v74, v16, v91
	v_cvt_pk_bf16_f32 v16, v66, v58
	v_lshlrev_b32_e32 v67, 16, v59
	v_lshlrev_b32_e32 v66, 16, v17
	v_pk_mul_f32 v[66:67], v[18:19], v[66:67]
	v_and_b32_e32 v59, 0xffff0000, v59
	v_add_f32_e32 v58, v70, v66
	v_fma_f32 v70, v76, v58, -v66
	v_sub_f32_e32 v71, v58, v71
	v_and_b32_e32 v58, 0xffff0000, v17
	v_pk_mul_f32 v[18:19], v[18:19], v[58:59]
	s_waitcnt vmcnt(1)
	v_lshlrev_b32_e32 v59, 16, v57
	v_add_f32_e32 v17, v50, v18
	v_fma_f32 v50, v76, v17, -v18
	v_sub_f32_e32 v75, v17, v51
	v_cvt_pk_bf16_f32 v17, v70, v50
	ds_write_b64 v0, v[16:17] offset:10320
	v_lshlrev_b32_e32 v17, 16, v56
	v_lshlrev_b32_e32 v16, 16, v8
	v_pk_mul_f32 v[16:17], v[6:7], v[16:17]
	v_and_b32_e32 v51, 0xffff0000, v56
	v_add_f32_e32 v50, v73, v16
	v_fma_f32 v58, v78, v50, -v16
	v_sub_f32_e32 v10, v50, v10
	v_and_b32_e32 v50, 0xffff0000, v8
	v_pk_mul_f32 v[50:51], v[6:7], v[50:51]
	v_and_b32_e32 v57, 0xffff0000, v57
	v_add_f32_e32 v8, v74, v50
	v_fma_f32 v56, v78, v8, -v50
	v_sub_f32_e32 v12, v8, v12
	v_cvt_pk_bf16_f32 v8, v58, v56
	v_lshlrev_b32_e32 v58, 16, v9
	v_pk_mul_f32 v[58:59], v[6:7], v[58:59]
	v_mul_f32_e32 v96, v72, v95
	v_add_f32_e32 v56, v71, v58
	v_fma_f32 v70, v78, v56, -v58
	v_sub_f32_e32 v24, v56, v24
	v_and_b32_e32 v56, 0xffff0000, v9
	v_pk_mul_f32 v[6:7], v[6:7], v[56:57]
	v_lshlrev_b32_e32 v92, 16, v68
	v_add_f32_e32 v9, v75, v6
	v_fma_f32 v56, v78, v9, -v6
	v_sub_f32_e32 v38, v9, v38
	v_cvt_pk_bf16_f32 v9, v70, v56
	ds_write_b64 v0, v[8:9] offset:12384
	s_waitcnt vmcnt(0)
	v_and_b32_e32 v9, 0xffff0000, v53
	v_and_b32_e32 v8, 0xffff0000, v3
	v_pk_mul_f32 v[8:9], v[4:5], v[8:9]
	v_and_b32_e32 v68, 0xffff0000, v68
	v_add_f32_e32 v38, v38, v8
	v_fma_f32 v56, v38, s10, -v8
	v_sub_f32_e32 v38, v38, v39
	v_fmac_f32_e32 v38, v72, v69
	v_fma_f32 v39, v38, s10, -v97
	v_sub_f32_e32 v38, v38, v42
	v_add_f32_e32 v38, v38, v43
	v_fma_f32 v42, v38, s10, -v43
	v_sub_f32_e32 v38, v38, v48
	v_add_f32_e32 v38, v38, v49
	v_sub_f32_e32 v32, v38, v32
	v_add_f32_e32 v32, v32, v33
	v_sub_f32_e32 v14, v32, v14
	v_add_f32_e32 v14, v14, v15
	v_fma_f32 v33, v32, s10, -v33
	v_fma_f32 v32, v14, s10, -v15
	v_sub_f32_e32 v14, v14, v18
	v_add_f32_e32 v14, v14, v19
	v_sub_f32_e32 v6, v14, v6
	v_add_f32_e32 v6, v6, v7
	v_fma_f32 v18, v14, s10, -v19
	v_fma_f32 v19, v6, s10, -v7
	v_sub_f32_e32 v6, v6, v8
	v_add_f32_e32 v8, v6, v9
	v_lshlrev_b32_e32 v7, 16, v53
	v_lshlrev_b32_e32 v6, 16, v3
	v_pk_mul_f32 v[6:7], v[4:5], v[6:7]
	v_fma_f32 v43, v38, s10, -v49
	v_add_f32_e32 v3, v24, v6
	v_fma_f32 v24, v3, s10, -v6
	v_sub_f32_e32 v3, v3, v25
	v_fmac_f32_e32 v3, v72, v95
	v_fma_f32 v25, v3, s10, -v96
	v_sub_f32_e32 v3, v3, v46
	v_add_f32_e32 v3, v3, v47
	v_fma_f32 v38, v3, s10, -v47
	v_sub_f32_e32 v3, v3, v44
	v_add_f32_e32 v3, v3, v45
	v_fma_f32 v44, v3, s10, -v45
	v_sub_f32_e32 v3, v3, v54
	v_add_f32_e32 v3, v3, v55
	v_fma_f32 v45, v3, s10, -v55
	v_sub_f32_e32 v3, v3, v64
	v_add_f32_e32 v3, v3, v65
	v_fma_f32 v46, v3, s10, -v65
	v_sub_f32_e32 v3, v3, v66
	v_add_f32_e32 v3, v3, v67
	v_fma_f32 v47, v3, s10, -v67
	v_sub_f32_e32 v3, v3, v58
	v_add_f32_e32 v3, v3, v59
	v_and_b32_e32 v15, 0xffff0000, v52
	v_and_b32_e32 v14, 0xffff0000, v2
	v_fma_f32 v48, v3, s10, -v59
	v_sub_f32_e32 v3, v3, v6
	v_pk_mul_f32 v[14:15], v[4:5], v[14:15]
	v_add_f32_e32 v6, v3, v7
	v_add_f32_e32 v3, v12, v14
	v_fma_f32 v12, v3, s10, -v14
	v_sub_f32_e32 v3, v3, v13
	v_mul_f32_e32 v94, v72, v68
	v_fmac_f32_e32 v3, v72, v68
	v_fma_f32 v13, v3, s10, -v94
	v_sub_f32_e32 v3, v3, v36
	v_add_f32_e32 v3, v3, v37
	v_fma_f32 v36, v3, s10, -v37
	v_sub_f32_e32 v3, v3, v40
	v_add_f32_e32 v3, v3, v41
	v_fma_f32 v37, v3, s10, -v41
	v_sub_f32_e32 v3, v3, v34
	v_add_f32_e32 v3, v3, v35
	v_fma_f32 v34, v3, s10, -v35
	v_sub_f32_e32 v3, v3, v62
	v_add_f32_e32 v3, v3, v63
	v_fma_f32 v35, v3, s10, -v63
	v_sub_f32_e32 v3, v3, v60
	v_add_f32_e32 v3, v3, v61
	v_fma_f32 v40, v3, s10, -v61
	v_sub_f32_e32 v3, v3, v50
	v_add_f32_e32 v3, v3, v51
	v_fma_f32 v41, v3, s10, -v51
	v_sub_f32_e32 v3, v3, v14
	v_add_f32_e32 v14, v3, v15
	v_lshlrev_b32_e32 v3, 16, v52
	v_lshlrev_b32_e32 v2, 16, v2
	v_pk_mul_f32 v[2:3], v[4:5], v[2:3]
	v_mul_f32_e32 v93, v72, v92
	v_add_f32_e32 v4, v10, v2
	v_fma_f32 v5, v4, s10, -v2
	v_sub_f32_e32 v4, v4, v11
	v_fmac_f32_e32 v4, v72, v92
	v_fma_f32 v10, v4, s10, -v93
	v_sub_f32_e32 v4, v4, v22
	v_add_f32_e32 v4, v4, v23
	v_fma_f32 v11, v4, s10, -v23
	v_sub_f32_e32 v4, v4, v28
	v_add_f32_e32 v4, v4, v29
	v_fma_f32 v22, v4, s10, -v29
	v_sub_f32_e32 v4, v4, v26
	v_add_f32_e32 v4, v4, v27
	v_fma_f32 v23, v4, s10, -v27
	v_sub_f32_e32 v4, v4, v30
	v_add_f32_e32 v4, v4, v31
	v_fma_f32 v26, v4, s10, -v31
	v_sub_f32_e32 v4, v4, v20
	v_add_f32_e32 v4, v4, v21
	v_fma_f32 v20, v4, s10, -v21
	v_sub_f32_e32 v16, v4, v16
	v_cvt_pk_bf16_f32 v4, v5, v12
	v_cvt_pk_bf16_f32 v5, v24, v56
	ds_write_b64 v0, v[4:5] offset:14448
	v_cvt_pk_bf16_f32 v4, v10, v13
	v_cvt_pk_bf16_f32 v5, v25, v39
	ds_write_b64 v0, v[4:5] offset:16512
	v_cvt_pk_bf16_f32 v4, v11, v36
	v_add_f32_e32 v12, v16, v17
	v_cvt_pk_bf16_f32 v5, v38, v42
	ds_write_b64 v0, v[4:5] offset:18576
	v_cvt_pk_bf16_f32 v4, v22, v37
	v_cvt_pk_bf16_f32 v5, v44, v43
	ds_write_b64 v0, v[4:5] offset:20640
	v_cvt_pk_bf16_f32 v4, v23, v34
	v_sub_f32_e32 v2, v12, v2
	v_cvt_pk_bf16_f32 v5, v45, v33
	ds_write_b64 v0, v[4:5] offset:22704
	v_cvt_pk_bf16_f32 v4, v26, v35
	v_add_f32_e32 v2, v2, v3
	v_cvt_pk_bf16_f32 v5, v46, v32
	ds_write_b64 v0, v[4:5] offset:24768
	v_cvt_pk_bf16_f32 v4, v20, v40
	v_fma_f32 v2, v2, s10, -v3
	v_fma_f32 v3, v14, s10, -v15
	v_fma_f32 v16, v12, s10, -v17
	v_cvt_pk_bf16_f32 v5, v47, v18
	ds_write_b64 v0, v[4:5] offset:26832
	v_cvt_pk_bf16_f32 v4, v16, v41
	v_cvt_pk_bf16_f32 v2, v2, v3
	v_fma_f32 v3, v6, s10, -v7
	v_cvt_pk_bf16_f32 v5, v48, v19
	ds_write_b64 v0, v[4:5] offset:28896
	v_fma_f32 v4, v8, s10, -v9
	v_cvt_pk_bf16_f32 v3, v3, v4

.LBB0_449:
	s_or_b32 s2, s40, 5
	s_cmp_gt_i32 s40, -6
	s_cselect_b32 s26, s2, s40
	s_ashr_i32 s27, s26, 31
	s_lshl_b64 s[18:19], s[26:27], 11
	v_lshl_add_u64 v[2:3], v[214:215], 0, s[18:19]
	global_load_dwordx2 v[28:29], v[2:3], off
	s_cmp_lt_i32 s40, -5
	v_mov_b32_e32 v10, 0
	v_mov_b32_e32 v30, 0
	s_cbranch_scc1 .LBB0_451
	s_lshl_b64 s[18:19], s[26:27], 2
	s_add_u32 s18, s86, s18
	s_addc_u32 s19, s87, s19
	global_load_dword v30, v1, s[18:19]

.LBB0_471:
	s_waitcnt vmcnt(10)
	v_lshlrev_b32_e32 v55, 16, v48
	v_lshlrev_b32_e32 v54, 16, v36
	v_and_b32_e32 v57, 0xffff0000, v48
	v_and_b32_e32 v56, 0xffff0000, v36
	s_cmpk_gt_i32 s40, 0x7fff
	v_pk_mul_f32 v[54:55], v[34:35], v[54:55]
	v_pk_mul_f32 v[56:57], v[34:35], v[56:57]
	v_lshlrev_b32_e32 v59, 16, v49
	v_lshlrev_b32_e32 v58, 16, v37
	v_and_b32_e32 v49, 0xffff0000, v49
	v_and_b32_e32 v48, 0xffff0000, v37
	v_add_f32_e32 v0, 0, v54
	v_add_f32_e32 v4, 0, v56
	v_pk_mul_f32 v[58:59], v[34:35], v[58:59]
	v_pk_mul_f32 v[34:35], v[34:35], v[48:49]
	s_cselect_b64 s[18:19], -1, 0
	v_add_f32_e32 v36, 0, v58
	v_add_f32_e32 v37, 0, v34
	v_add_f32_e32 v48, v0, v55
	v_add_f32_e32 v4, v4, v57
	v_cndmask_b32_e64 v0, 0.5, 1.0, s[18:19]
	v_add_f32_e32 v49, v36, v59
	v_add_f32_e32 v60, v37, v35
	v_fma_f32 v36, v0, v48, -v55
	v_fma_f32 v37, v0, v4, -v57
	v_cvt_pk_bf16_f32 v36, v36, v37
	v_fma_f32 v37, v0, v49, -v59
	v_fma_f32 v0, v0, v60, -v35
	v_cvt_pk_bf16_f32 v37, v37, v0
	v_add_u32_e32 v0, s16, v242
	ds_write_b64 v0, v[36:37]
	v_lshlrev_b32_e32 v37, 16, v52
	v_lshlrev_b32_e32 v36, 16, v32
	v_sub_f32_e32 v48, v48, v54
	v_pk_mul_f32 v[36:37], v[38:39], v[36:37]
	v_sub_f32_e32 v4, v4, v56
	v_add_f32_e32 v48, v48, v36
	v_sub_f32_e32 v56, v49, v58
	v_fma_f32 v54, v48, 0.5, -v36
	v_sub_f32_e32 v58, v48, v55
	v_and_b32_e32 v49, 0xffff0000, v52
	v_and_b32_e32 v48, 0xffff0000, v32
	v_pk_mul_f32 v[48:49], v[38:39], v[48:49]
	v_lshlrev_b32_e32 v55, 16, v53
	v_add_f32_e32 v4, v4, v48
	v_fma_f32 v32, v4, 0.5, -v48
	v_cvt_pk_bf16_f32 v32, v54, v32
	v_lshlrev_b32_e32 v54, 16, v33
	v_pk_mul_f32 v[54:55], v[38:39], v[54:55]
	v_sub_f32_e32 v4, v4, v57
	v_add_f32_e32 v52, v56, v54
	v_fma_f32 v56, v52, 0.5, -v54
	v_sub_f32_e32 v57, v52, v59
	v_and_b32_e32 v53, 0xffff0000, v53
	v_and_b32_e32 v52, 0xffff0000, v33
	v_sub_f32_e32 v34, v60, v34
	v_pk_mul_f32 v[38:39], v[38:39], v[52:53]
	v_lshlrev_b32_e32 v53, 16, v47
	v_add_f32_e32 v33, v34, v38
	v_fma_f32 v34, v33, 0.5, -v38
	v_sub_f32_e32 v59, v33, v35
	v_cvt_pk_bf16_f32 v33, v56, v34
	ds_write_b64 v0, v[32:33] offset:2064
	v_lshlrev_b32_e32 v33, 16, v46
	v_lshlrev_b32_e32 v32, 16, v24
	v_pk_mul_f32 v[32:33], v[14:15], v[32:33]
	v_and_b32_e32 v35, 0xffff0000, v46
	v_add_f32_e32 v34, v58, v32
	v_fma_f32 v52, v34, 0.5, -v32
	v_sub_f32_e32 v34, v34, v36
	v_add_f32_e32 v34, v34, v37
	v_fma_f32 v36, v34, 0.5, -v37
	v_sub_f32_e32 v32, v34, v32
	v_and_b32_e32 v34, 0xffff0000, v24
	v_pk_mul_f32 v[34:35], v[14:15], v[34:35]
	v_and_b32_e32 v47, 0xffff0000, v47
	v_add_f32_e32 v4, v4, v34
	v_fma_f32 v24, v4, 0.5, -v34
	v_cvt_pk_bf16_f32 v24, v52, v24
	v_lshlrev_b32_e32 v52, 16, v25
	v_and_b32_e32 v46, 0xffff0000, v25
	v_sub_f32_e32 v4, v4, v48
	v_pk_mul_f32 v[52:53], v[14:15], v[52:53]
	v_pk_mul_f32 v[14:15], v[14:15], v[46:47]
	v_add_f32_e32 v4, v4, v49
	v_add_f32_e32 v25, v59, v14
	v_fma_f32 v48, v4, 0.5, -v49
	v_sub_f32_e32 v4, v4, v34
	v_add_f32_e32 v34, v57, v52
	v_fma_f32 v46, v25, 0.5, -v14
	v_sub_f32_e32 v25, v25, v38
	v_fma_f32 v56, v34, 0.5, -v52
	v_sub_f32_e32 v34, v34, v54
	v_add_f32_e32 v25, v25, v39
	v_add_f32_e32 v34, v34, v55
	v_fma_f32 v38, v25, 0.5, -v39
	v_sub_f32_e32 v14, v25, v14
	v_cvt_pk_bf16_f32 v25, v56, v46
	v_fma_f32 v54, v34, 0.5, -v55
	v_sub_f32_e32 v34, v34, v52
	ds_write_b64 v0, v[24:25] offset:4128
	v_cvt_pk_bf16_f32 v24, v36, v48
	v_cvt_pk_bf16_f32 v25, v54, v38
	v_add_f32_e32 v32, v32, v33
	v_add_f32_e32 v4, v4, v35
	ds_write_b64 v0, v[24:25] offset:6192
	v_add_f32_e32 v34, v34, v53
	v_fma_f32 v24, v32, 0.5, -v33
	v_fma_f32 v25, v4, 0.5, -v35
	v_add_f32_e32 v14, v14, v15
	v_cvt_pk_bf16_f32 v24, v24, v25
	v_fma_f32 v25, v34, 0.5, -v53
	v_fma_f32 v36, v14, 0.5, -v15
	v_cvt_pk_bf16_f32 v25, v25, v36
	ds_write_b64 v0, v[24:25] offset:8256
	s_waitcnt vmcnt(8)
	v_lshlrev_b32_e32 v25, 16, v50
	v_lshlrev_b32_e32 v24, 16, v28
	v_sub_f32_e32 v32, v32, v37
	v_pk_mul_f32 v[24:25], v[30:31], v[24:25]
	v_sub_f32_e32 v38, v14, v39
	v_add_f32_e32 v14, v32, v24
	v_sub_f32_e32 v39, v14, v33
	v_and_b32_e32 v33, 0xffff0000, v50
	v_and_b32_e32 v32, 0xffff0000, v28
	v_sub_f32_e32 v4, v4, v49
	v_pk_mul_f32 v[32:33], v[30:31], v[32:33]
	v_sub_f32_e32 v36, v34, v55
	v_add_f32_e32 v4, v4, v32
	v_fma_f32 v34, v14, 0.5, -v24
	v_fma_f32 v14, v4, 0.5, -v32
	v_sub_f32_e32 v4, v4, v35
	v_cvt_pk_bf16_f32 v14, v34, v14
	v_lshlrev_b32_e32 v35, 16, v51
	v_lshlrev_b32_e32 v34, 16, v29
	v_pk_mul_f32 v[34:35], v[30:31], v[34:35]
	v_and_b32_e32 v37, 0xffff0000, v51
	v_add_f32_e32 v28, v36, v34
	v_and_b32_e32 v36, 0xffff0000, v29
	v_fma_f32 v46, v28, 0.5, -v34
	v_sub_f32_e32 v47, v28, v53
	v_pk_mul_f32 v[28:29], v[30:31], v[36:37]
	s_waitcnt vmcnt(7)
	v_lshlrev_b32_e32 v37, 16, v43
	v_add_f32_e32 v30, v38, v28
	v_fma_f32 v31, v30, 0.5, -v28
	v_sub_f32_e32 v48, v30, v15
	v_cvt_pk_bf16_f32 v15, v46, v31
	ds_write_b64 v0, v[14:15] offset:10320
	v_lshlrev_b32_e32 v15, 16, v42
	v_lshlrev_b32_e32 v14, 16, v18
	v_pk_mul_f32 v[14:15], v[10:11], v[14:15]
	v_and_b32_e32 v31, 0xffff0000, v42
	v_add_f32_e32 v30, v39, v14
	v_fma_f32 v36, v30, 0.5, -v14
	v_sub_f32_e32 v24, v30, v24
	v_and_b32_e32 v30, 0xffff0000, v18
	v_pk_mul_f32 v[30:31], v[10:11], v[30:31]
	v_add_f32_e32 v24, v24, v25
	v_add_f32_e32 v4, v4, v30
	v_fma_f32 v18, v4, 0.5, -v30
	v_sub_f32_e32 v4, v4, v32
	v_cvt_pk_bf16_f32 v18, v36, v18
	v_lshlrev_b32_e32 v36, 16, v19
	v_add_f32_e32 v4, v4, v33
	v_pk_mul_f32 v[36:37], v[10:11], v[36:37]
	v_fma_f32 v46, v24, 0.5, -v25
	v_sub_f32_e32 v14, v24, v14
	v_fma_f32 v24, v4, 0.5, -v33
	v_sub_f32_e32 v4, v4, v30
	v_add_f32_e32 v30, v47, v36
	v_and_b32_e32 v39, 0xffff0000, v43
	v_and_b32_e32 v38, 0xffff0000, v19
	v_fma_f32 v32, v30, 0.5, -v36
	v_sub_f32_e32 v30, v30, v34
	v_pk_mul_f32 v[10:11], v[10:11], v[38:39]
	v_add_f32_e32 v30, v30, v35
	v_add_f32_e32 v19, v48, v10
	v_fma_f32 v34, v30, 0.5, -v35
	v_sub_f32_e32 v30, v30, v36
	v_fma_f32 v36, v19, 0.5, -v10
	v_sub_f32_e32 v19, v19, v28
	v_add_f32_e32 v19, v19, v29
	v_fma_f32 v28, v19, 0.5, -v29
	v_sub_f32_e32 v10, v19, v10
	v_cvt_pk_bf16_f32 v19, v32, v36
	ds_write_b64 v0, v[18:19] offset:12384
	v_cvt_pk_bf16_f32 v18, v46, v24
	v_cvt_pk_bf16_f32 v19, v34, v28
	v_add_f32_e32 v14, v14, v15
	v_add_f32_e32 v4, v4, v31
	ds_write_b64 v0, v[18:19] offset:14448
	v_add_f32_e32 v24, v30, v37
	v_fma_f32 v18, v14, 0.5, -v15
	v_fma_f32 v19, v4, 0.5, -v31
	v_add_f32_e32 v10, v10, v11
	v_cvt_pk_bf16_f32 v18, v18, v19
	v_fma_f32 v19, v24, 0.5, -v37
	v_fma_f32 v28, v10, 0.5, -v11
	v_cvt_pk_bf16_f32 v19, v19, v28
	ds_write_b64 v0, v[18:19] offset:16512
	s_waitcnt vmcnt(4)
	v_lshlrev_b32_e32 v19, 16, v44
	v_lshlrev_b32_e32 v18, 16, v20
	v_sub_f32_e32 v14, v14, v25
	v_pk_mul_f32 v[18:19], v[22:23], v[18:19]
	v_sub_f32_e32 v30, v10, v29
	v_add_f32_e32 v10, v14, v18
	v_sub_f32_e32 v34, v10, v15
	v_and_b32_e32 v15, 0xffff0000, v44
	v_and_b32_e32 v14, 0xffff0000, v20
	v_sub_f32_e32 v4, v4, v33
	v_pk_mul_f32 v[14:15], v[22:23], v[14:15]
	v_sub_f32_e32 v28, v24, v35
	v_add_f32_e32 v4, v4, v14
	v_fma_f32 v24, v10, 0.5, -v18
	v_fma_f32 v10, v4, 0.5, -v14
	v_cvt_pk_bf16_f32 v10, v24, v10
	v_lshlrev_b32_e32 v25, 16, v45
	v_lshlrev_b32_e32 v24, 16, v21
	v_pk_mul_f32 v[24:25], v[22:23], v[24:25]
	v_lshlrev_b32_e32 v32, 16, v13
	v_add_f32_e32 v20, v28, v24
	v_sub_f32_e32 v4, v4, v31
	v_fma_f32 v31, v20, 0.5, -v24
	v_sub_f32_e32 v20, v20, v37
	v_mul_f32_e32 v29, v2, v32
	v_fmac_f32_e32 v20, v2, v32
	v_fma_f32 v35, v20, 0.5, -v29
	v_and_b32_e32 v29, 0xffff0000, v45
	v_and_b32_e32 v28, 0xffff0000, v21
	v_sub_f32_e32 v24, v20, v24
	v_pk_mul_f32 v[20:21], v[22:23], v[28:29]
	v_and_b32_e32 v13, 0xffff0000, v13
	v_add_f32_e32 v22, v30, v20
	v_sub_f32_e32 v11, v22, v11
	v_mul_f32_e32 v33, v2, v13
	v_fmac_f32_e32 v11, v2, v13
	v_fma_f32 v23, v22, 0.5, -v20
	v_fma_f32 v28, v11, 0.5, -v33
	v_sub_f32_e32 v20, v11, v20
	v_cvt_pk_bf16_f32 v11, v31, v23
	ds_write_b64 v0, v[10:11] offset:18576
	v_add_f32_e32 v10, v24, v25
	v_add_f32_e32 v11, v20, v21
	v_fma_f32 v20, v10, 0.5, -v25
	v_fma_f32 v24, v11, 0.5, -v21
	v_fma_f32 v29, -v2, v32, v10
	v_fma_f32 v30, -v2, v13, v11
	s_waitcnt vmcnt(3)
	v_lshlrev_b32_e32 v11, 16, v16
	v_lshlrev_b32_e32 v10, 16, v12
	v_pk_mul_f32 v[10:11], v[2:3], v[10:11]
	v_and_b32_e32 v12, 0xffff0000, v12
	v_add_f32_e32 v13, v34, v10
	v_fma_f32 v22, v13, 0.5, -v10
	v_sub_f32_e32 v13, v13, v18
	v_add_f32_e32 v13, v13, v19
	v_fma_f32 v18, v13, 0.5, -v19
	v_sub_f32_e32 v10, v13, v10
	v_and_b32_e32 v13, 0xffff0000, v16
	v_pk_mul_f32 v[12:13], v[2:3], v[12:13]
	v_cvt_pk_bf16_f32 v23, v35, v28
	s_mov_b64 s[26:27], 0
	v_add_f32_e32 v2, v4, v12
	v_fma_f32 v4, v2, 0.5, -v12
	v_sub_f32_e32 v2, v2, v14
	v_add_f32_e32 v2, v2, v15
	v_fma_f32 v14, v2, 0.5, -v15
	v_sub_f32_e32 v2, v2, v12
	v_cvt_pk_bf16_f32 v22, v22, v4
	v_add_f32_e32 v4, v10, v11
	v_add_f32_e32 v10, v2, v13
	v_fma_f32 v2, v4, 0.5, -v11
	v_fma_f32 v12, v10, 0.5, -v13
	ds_write_b64 v0, v[22:23] offset:20640
	v_cvt_pk_bf16_f32 v22, v18, v14
	v_cvt_pk_bf16_f32 v2, v2, v12
	v_sub_f32_e32 v12, v4, v19
	v_sub_f32_e32 v10, v10, v15
	s_waitcnt vmcnt(1)
	v_lshlrev_b32_e32 v15, 16, v41
	v_lshlrev_b32_e32 v14, 16, v17
	v_mov_b32_e32 v4, v3
	v_pk_mul_f32 v[14:15], v[4:5], v[14:15]
	v_and_b32_e32 v19, 0xffff0000, v41
	v_and_b32_e32 v18, 0xffff0000, v17
	v_add_f32_e32 v3, v29, v14
	v_pk_mul_f32 v[16:17], v[4:5], v[18:19]
	v_fma_f32 v28, v3, 0.5, -v14
	v_sub_f32_e32 v25, v3, v25
	v_add_f32_e32 v3, v30, v16
	v_fma_f32 v4, v3, 0.5, -v16
	v_sub_f32_e32 v18, v3, v21
	v_cvt_pk_bf16_f32 v3, v28, v4
	ds_write_b64 v0, v[2:3] offset:24768
	s_waitcnt vmcnt(0)
	v_and_b32_e32 v3, 0xffff0000, v27
	v_and_b32_e32 v2, 0xffff0000, v7
	v_pk_mul_f32 v[2:3], v[8:9], v[2:3]
	v_cvt_pk_bf16_f32 v23, v20, v24
	ds_write_b64 v0, v[22:23] offset:22704
	v_add_f32_e32 v4, v18, v2
	v_fma_f32 v18, v4, 0.5, -v2
	v_sub_f32_e32 v4, v4, v16
	v_add_f32_e32 v4, v4, v17
	v_fma_f32 v19, v4, 0.5, -v17
	v_lshlrev_b32_e32 v17, 16, v27
	v_lshlrev_b32_e32 v16, 16, v7
	v_sub_f32_e32 v2, v4, v2
	v_pk_mul_f32 v[16:17], v[8:9], v[16:17]
	v_add_f32_e32 v21, v2, v3
	v_add_f32_e32 v2, v25, v16
	v_fma_f32 v25, v2, 0.5, -v16
	v_sub_f32_e32 v2, v2, v14
	v_add_f32_e32 v2, v2, v15
	v_fma_f32 v27, v2, 0.5, -v15
	v_and_b32_e32 v15, 0xffff0000, v26
	v_and_b32_e32 v14, 0xffff0000, v6
	v_lshlrev_b32_e32 v7, 16, v26
	v_lshlrev_b32_e32 v6, 16, v6
	v_sub_f32_e32 v2, v2, v16
	v_pk_mul_f32 v[14:15], v[8:9], v[14:15]
	v_pk_mul_f32 v[6:7], v[8:9], v[6:7]
	v_add_f32_e32 v16, v2, v17
	v_add_f32_e32 v2, v10, v14
	v_add_f32_e32 v8, v12, v6
	v_lshlrev_b32_e32 v20, 16, v40
	v_and_b32_e32 v23, 0xffff0000, v40
	v_fma_f32 v4, v2, 0.5, -v14
	v_sub_f32_e32 v2, v2, v13
	v_fma_f32 v9, v8, 0.5, -v6
	v_sub_f32_e32 v8, v8, v11
	v_mul_f32_e32 v22, v5, v20
	v_mul_f32_e32 v24, v5, v23
	v_fmac_f32_e32 v2, v5, v23
	v_cvt_pk_bf16_f32 v4, v9, v4
	v_fmac_f32_e32 v8, v5, v20
	v_fma_f32 v10, v2, 0.5, -v24
	v_fma_f32 v9, v8, 0.5, -v22
	v_cvt_pk_bf16_f32 v5, v25, v18
	ds_write_b64 v0, v[4:5] offset:26832
	v_cvt_pk_bf16_f32 v4, v9, v10
	v_sub_f32_e32 v2, v2, v14
	v_cvt_pk_bf16_f32 v5, v27, v19
	ds_write_b64 v0, v[4:5] offset:28896
	v_sub_f32_e32 v4, v8, v6
	v_add_f32_e32 v2, v2, v15
	v_add_f32_e32 v4, v4, v7
	v_fma_f32 v4, v4, 0.5, -v7
	v_fma_f32 v2, v2, 0.5, -v15
	v_fma_f32 v3, v21, 0.5, -v3
	v_cvt_pk_bf16_f32 v2, v4, v2
	v_fma_f32 v4, v16, 0.5, -v17
	v_cvt_pk_bf16_f32 v3, v4, v3
.LBB0_472:
	s_and_b64 vcc, exec, s[26:27]
	s_cbranch_vccz .LBB0_320
	s_add_i32 s2, s40, 0xffff8000
	s_and_b32 s6, s40, 0x7f0
	s_add_i32 s17, s40, -3
	s_cmp_lt_i32 s40, 0x8000
	s_cselect_b64 s[26:27], -1, 0
	s_and_b64 s[18:19], s[26:27], exec
	s_cselect_b32 s2, s6, s2
	s_cselect_b32 s6, 0x800d, -1
	s_cmp_eq_u32 s2, 0
	s_cselect_b64 s[50:51], -1, 0
	s_and_b64 s[18:19], s[50:51], exec
	s_cselect_b32 s2, s6, s17
	s_cmp_gt_i32 s2, -1
	s_cselect_b32 s58, s2, s40
	s_ashr_i32 s59, s58, 31
	s_lshl_b64 s[18:19], s[58:59], 11
	s_waitcnt lgkmcnt(0)
	v_lshl_add_u64 v[2:3], v[214:215], 0, s[18:19]
	global_load_dwordx2 v[30:31], v[2:3], off
	s_cmp_lt_i32 s2, 0
	v_mov_b32_e32 v29, 0
	v_mov_b32_e32 v28, 0
	s_cbranch_scc1 .LBB0_475
	s_lshl_b64 s[18:19], s[58:59], 2
	s_add_u32 s18, s86, s18
	s_addc_u32 s19, s87, s19
	global_load_dword v28, v1, s[18:19]
